# baseline ml_k2 q.n dot product re-issued with all LDS reads in flight and two interleaved FMA chains; gdn_k2 loads interleaved again; packed-FMA gdn_k1 solve
# speedup vs baseline: 1.0130x; 1.0026x over previous
.LBB0_465:
	s_waitcnt vmcnt(18)
	v_mov_b32_e32 v138, v119
	v_ashrrev_i32_e32 v119, 31, v118
	ds_write_b128 v133, v[2:5]
	ds_write_b128 v133, v[6:9] offset:9216
	ds_write_b128 v133, v[10:13] offset:18432
	ds_write_b128 v133, v[14:17] offset:27648
	ds_write_b128 v132, v[18:21]
	ds_write_b128 v132, v[22:25] offset:9216
	ds_write_b128 v132, v[26:29] offset:18432
	ds_write_b128 v132, v[30:33] offset:27648
	v_lshlrev_b64 v[2:3], 13, v[118:119]
	v_lshl_add_u64 v[2:3], s[30:31], 0, v[2:3]
	s_lshl_b32 s2, s41, 1
	v_lshl_add_u64 v[2:3], v[2:3], 0, s[2:3]
	v_lshl_add_u64 v[2:3], v[2:3], 0, v[0:1]
	v_add_co_u32_e32 v2, vcc, s93, v2
	v_lshl_add_u64 v[14:15], s[24:25], 0, v[112:113]
	s_nop 0
	v_addc_co_u32_e32 v3, vcc, 0, v3, vcc
	v_add_co_u32_e32 v6, vcc, s4, v14
	s_waitcnt vmcnt(16)
	v_mov_b32_e32 v121, v117
	v_addc_co_u32_e32 v7, vcc, 0, v15, vcc
	v_ashrrev_i32_e32 v117, 31, v116
	v_add_co_u32_e32 v10, vcc, s5, v14
	v_lshlrev_b64 v[18:19], 13, v[116:117]
	s_nop 0
	v_addc_co_u32_e32 v11, vcc, 0, v15, vcc
	v_lshl_add_u64 v[18:19], s[30:31], 0, v[18:19]
	v_add_co_u32_e32 v14, vcc, s6, v14
	v_lshl_add_u64 v[18:19], v[18:19], 0, s[2:3]
	s_nop 0
	v_addc_co_u32_e32 v15, vcc, 0, v15, vcc
	v_lshl_add_u64 v[18:19], v[18:19], 0, v[0:1]
	v_add_co_u32_e32 v18, vcc, s93, v18
	v_lshl_add_u64 v[30:31], s[24:25], 0, v[114:115]
	s_nop 0
	v_addc_co_u32_e32 v19, vcc, 0, v19, vcc
	v_add_co_u32_e32 v22, vcc, s4, v30
	v_lshl_add_u64 v[34:35], s[24:25], 0, v[110:111]
	s_nop 0
	v_addc_co_u32_e32 v23, vcc, 0, v31, vcc
	v_add_co_u32_e32 v26, vcc, s5, v30
	s_mov_b32 s44, 0x3000000
	s_nop 0
	v_addc_co_u32_e32 v27, vcc, 0, v31, vcc
	v_add_co_u32_e32 v30, vcc, s6, v30
	v_mov_b32_e32 v36, v134
	s_nop 0
	v_addc_co_u32_e32 v31, vcc, 0, v31, vcc
	v_add_co_u32_e32 v34, vcc, s44, v34
	v_mov_b32_e32 v66, v131
	s_nop 0
	v_addc_co_u32_e32 v35, vcc, 0, v35, vcc
	v_mov_b32_e32 v67, v130
	s_waitcnt lgkmcnt(0)
	s_barrier
	global_load_dwordx4 v[2:5], v[2:3], off offset:1552
	v_max_f32_e32 v139, v83, v83
	global_load_dwordx4 v[6:9], v[6:7], off
	s_add_u32 s44, s24, s42
	global_load_dwordx4 v[10:13], v[10:11], off
	v_mov_b32_e32 v120, v125
	global_load_dwordx4 v[14:17], v[14:15], off
	s_addc_u32 s45, s25, s43
	global_load_dwordx4 v[18:21], v[18:19], off offset:1552
	v_add_u32_e32 v136, 0x800, v127
	global_load_dwordx4 v[22:25], v[22:23], off
	v_add_u32_e32 v135, 0x1000, v127
	global_load_dwordx4 v[26:29], v[26:27], off
	v_add_u32_e32 v137, 0x1800, v127
	global_load_dwordx4 v[30:33], v[30:31], off
	s_nop 0
	global_load_dword v131, v[34:35], off offset:1280
	global_load_dword v134, v[34:35], off offset:1536
	global_load_dword v130, v[34:35], off offset:1792
	global_load_dword v119, v[34:35], off offset:2048
	v_max_f32_e32 v34, v36, v36
	v_max_f32_e32 v68, v139, v34
	v_sub_f32_e32 v34, v83, v68
	global_load_dword v125, v148, s[44:45] offset:2304
	global_load_dword v117, v148, s[44:45] offset:1532
	ds_write_b32 v128, v82 offset:36864
	v_mul_f32_e32 v69, 0x3fb8aa3b, v34
	v_sub_f32_e32 v34, v120, v68
	v_mul_f32_e32 v70, 0x3fb8aa3b, v34
	s_mov_b64 s[44:45], 0x500
	v_lshl_add_u64 v[110:111], v[110:111], 0, s[44:45]
	v_lshl_add_u64 v[112:113], v[112:113], 0, s[8:9]
	v_lshl_add_u64 v[114:115], v[114:115], 0, s[8:9]
	v_add_u32_e32 v116, 64, v116
	v_add_u32_e32 v118, 64, v118
	ds_read_b128 v[34:37], v107
	ds_read_b128 v[38:41], v129 offset:36864
	ds_read_b128 v[42:45], v129 offset:36880
	ds_read_b128 v[46:49], v107 offset:16
	ds_read_b128 v[50:53], v129 offset:36896
	ds_read_b128 v[54:57], v129 offset:36912
	ds_read_b128 v[58:61], v107 offset:32
	ds_read_b128 v[62:65], v129 offset:36928
	ds_read_b128 v[208:211], v129 offset:36944
	ds_read_b128 v[212:215], v107 offset:48
	ds_read_b128 v[216:219], v129 offset:36960
	ds_read_b128 v[220:223], v129 offset:36976
	ds_read_b128 v[224:227], v107 offset:64
	ds_read_b128 v[228:231], v129 offset:36992
	ds_read_b128 v[232:235], v129 offset:37008
	s_waitcnt lgkmcnt(9)
	v_and_b32_e32 v254, 0xffff0000, v34
	v_and_b32_e32 v236, 0xffff0000, v46
	v_mul_f32_e32 v252, v39, v254
	v_mul_f32_e32 v253, v51, v236
	v_lshlrev_b32_e32 v71, 16, v34
	v_lshlrev_b32_e32 v237, 16, v46
	v_fmac_f32_e32 v252, v38, v71
	v_fmac_f32_e32 v253, v50, v237
	v_lshlrev_b32_e32 v254, 16, v35
	v_lshlrev_b32_e32 v236, 16, v47
	v_fmac_f32_e32 v252, v40, v254
	v_fmac_f32_e32 v253, v52, v236
	v_and_b32_e32 v71, 0xffff0000, v35
	v_and_b32_e32 v237, 0xffff0000, v47
	v_fmac_f32_e32 v252, v41, v71
	v_fmac_f32_e32 v253, v53, v237
	v_lshlrev_b32_e32 v254, 16, v36
	v_lshlrev_b32_e32 v236, 16, v48
	v_fmac_f32_e32 v252, v42, v254
	v_fmac_f32_e32 v253, v54, v236
	v_and_b32_e32 v71, 0xffff0000, v36
	v_and_b32_e32 v237, 0xffff0000, v48
	v_fmac_f32_e32 v252, v43, v71
	v_fmac_f32_e32 v253, v55, v237
	v_lshlrev_b32_e32 v254, 16, v37
	v_lshlrev_b32_e32 v236, 16, v49
	v_fmac_f32_e32 v252, v44, v254
	v_fmac_f32_e32 v253, v56, v236
	v_and_b32_e32 v71, 0xffff0000, v37
	v_and_b32_e32 v237, 0xffff0000, v49
	v_fmac_f32_e32 v252, v45, v71
	v_fmac_f32_e32 v253, v57, v237
	v_add_f32_e32 v242, 0, v252
	v_add_f32_e32 v242, v242, v253
	ds_read_b128 v[34:37], v107 offset:80
	ds_read_b128 v[38:41], v129 offset:37024
	ds_read_b128 v[42:45], v129 offset:37040
	ds_read_b128 v[46:49], v107 offset:96
	ds_read_b128 v[50:53], v129 offset:37056
	ds_read_b128 v[54:57], v129 offset:37072
	s_waitcnt lgkmcnt(9)
	v_and_b32_e32 v254, 0xffff0000, v58
	v_and_b32_e32 v236, 0xffff0000, v212
	v_mul_f32_e32 v252, v63, v254
	v_mul_f32_e32 v253, v217, v236
	v_lshlrev_b32_e32 v71, 16, v58
	v_lshlrev_b32_e32 v237, 16, v212
	v_fmac_f32_e32 v252, v62, v71
	v_fmac_f32_e32 v253, v216, v237
	v_lshlrev_b32_e32 v254, 16, v59
	v_lshlrev_b32_e32 v236, 16, v213
	v_fmac_f32_e32 v252, v64, v254
	v_fmac_f32_e32 v253, v218, v236
	v_and_b32_e32 v71, 0xffff0000, v59
	v_and_b32_e32 v237, 0xffff0000, v213
	v_fmac_f32_e32 v252, v65, v71
	v_fmac_f32_e32 v253, v219, v237
	v_lshlrev_b32_e32 v254, 16, v60
	v_lshlrev_b32_e32 v236, 16, v214
	v_fmac_f32_e32 v252, v208, v254
	v_fmac_f32_e32 v253, v220, v236
	v_and_b32_e32 v71, 0xffff0000, v60
	v_and_b32_e32 v237, 0xffff0000, v214
	v_fmac_f32_e32 v252, v209, v71
	v_fmac_f32_e32 v253, v221, v237
	v_lshlrev_b32_e32 v254, 16, v61
	v_lshlrev_b32_e32 v236, 16, v215
	v_fmac_f32_e32 v252, v210, v254
	v_fmac_f32_e32 v253, v222, v236
	v_and_b32_e32 v71, 0xffff0000, v61
	v_and_b32_e32 v237, 0xffff0000, v215
	v_fmac_f32_e32 v252, v211, v71
	v_fmac_f32_e32 v253, v223, v237
	v_add_f32_e32 v242, v242, v252
	v_add_f32_e32 v242, v242, v253
	ds_read_b128 v[58:61], v107 offset:112
	ds_read_b128 v[62:65], v129 offset:37088
	ds_read_b128 v[208:211], v129 offset:37104
	s_waitcnt lgkmcnt(6)
	v_and_b32_e32 v254, 0xffff0000, v224
	v_and_b32_e32 v236, 0xffff0000, v34
	v_mul_f32_e32 v252, v229, v254
	v_mul_f32_e32 v253, v39, v236
	v_lshlrev_b32_e32 v71, 16, v224
	v_lshlrev_b32_e32 v237, 16, v34
	v_fmac_f32_e32 v252, v228, v71
	v_fmac_f32_e32 v253, v38, v237
	v_lshlrev_b32_e32 v254, 16, v225
	v_lshlrev_b32_e32 v236, 16, v35
	v_fmac_f32_e32 v252, v230, v254
	v_fmac_f32_e32 v253, v40, v236
	v_and_b32_e32 v71, 0xffff0000, v225
	v_and_b32_e32 v237, 0xffff0000, v35
	v_fmac_f32_e32 v252, v231, v71
	v_fmac_f32_e32 v253, v41, v237
	v_lshlrev_b32_e32 v254, 16, v226
	v_lshlrev_b32_e32 v236, 16, v36
	v_fmac_f32_e32 v252, v232, v254
	v_fmac_f32_e32 v253, v42, v236
	v_and_b32_e32 v71, 0xffff0000, v226
	v_and_b32_e32 v237, 0xffff0000, v36
	v_fmac_f32_e32 v252, v233, v71
	v_fmac_f32_e32 v253, v43, v237
	v_lshlrev_b32_e32 v254, 16, v227
	v_lshlrev_b32_e32 v236, 16, v37
	v_fmac_f32_e32 v252, v234, v254
	v_fmac_f32_e32 v253, v44, v236
	v_and_b32_e32 v71, 0xffff0000, v227
	v_and_b32_e32 v237, 0xffff0000, v37
	v_fmac_f32_e32 v252, v235, v71
	v_fmac_f32_e32 v253, v45, v237
	v_add_f32_e32 v242, v242, v252
	v_add_f32_e32 v242, v242, v253
	s_waitcnt lgkmcnt(0)
	v_and_b32_e32 v254, 0xffff0000, v46
	v_and_b32_e32 v236, 0xffff0000, v58
	v_mul_f32_e32 v252, v51, v254
	v_mul_f32_e32 v253, v63, v236
	v_lshlrev_b32_e32 v71, 16, v46
	v_lshlrev_b32_e32 v237, 16, v58
	v_fmac_f32_e32 v252, v50, v71
	v_fmac_f32_e32 v253, v62, v237
	v_lshlrev_b32_e32 v254, 16, v47
	v_lshlrev_b32_e32 v236, 16, v59
	v_fmac_f32_e32 v252, v52, v254
	v_fmac_f32_e32 v253, v64, v236
	v_and_b32_e32 v71, 0xffff0000, v47
	v_and_b32_e32 v237, 0xffff0000, v59
	v_fmac_f32_e32 v252, v53, v71
	v_fmac_f32_e32 v253, v65, v237
	v_lshlrev_b32_e32 v254, 16, v48
	v_lshlrev_b32_e32 v236, 16, v60
	v_fmac_f32_e32 v252, v54, v254
	v_fmac_f32_e32 v253, v208, v236
	v_and_b32_e32 v71, 0xffff0000, v48
	v_and_b32_e32 v237, 0xffff0000, v60
	v_fmac_f32_e32 v252, v55, v71
	v_fmac_f32_e32 v253, v209, v237
	v_lshlrev_b32_e32 v254, 16, v49
	v_lshlrev_b32_e32 v236, 16, v61
	v_fmac_f32_e32 v252, v56, v254
	v_fmac_f32_e32 v253, v210, v236
	v_and_b32_e32 v71, 0xffff0000, v49
	v_and_b32_e32 v237, 0xffff0000, v61
	v_fmac_f32_e32 v252, v57, v71
	v_fmac_f32_e32 v253, v211, v237
	v_add_f32_e32 v242, v242, v252
	v_mov_b32_e32 v46, v242
	v_mov_b32_e32 v34, v253
	v_exp_f32_e32 v35, v69
	v_add_f32_e32 v37, v68, v66
	v_exp_f32_e32 v36, v70
	v_mul_f32_e32 v37, 0xbfb8aa3b, v37
	v_exp_f32_e32 v37, v37
	v_add_f32_e32 v34, v46, v34
	v_mul_f32_e32 v34, v35, v34
	v_fmac_f32_e32 v34, v67, v36
	v_max_f32_e64 v34, |v34|, v37
	v_rcp_f32_e32 v34, v34
	v_cvt_pk_bf16_f32 v37, v94, v95
	v_mul_f32_e32 v35, v35, v34
	v_mul_f32_e32 v34, v36, v34
	ds_write2st64_b32 v128, v35, v34 offset0:145 offset1:146
	ds_read2_b64 v[38:41], v127 offset1:4
	ds_read2_b64 v[42:45], v136 offset0:32 offset1:36
	ds_read2_b64 v[46:49], v135 offset0:64 offset1:68
	ds_read2_b64 v[50:53], v137 offset0:96 offset1:100
	ds_read2_b64 v[54:57], v127 offset0:8 offset1:12
	v_cvt_pk_bf16_f32 v34, v96, v97
	v_cvt_pk_bf16_f32 v35, v98, v99
	v_cvt_pk_bf16_f32 v36, v92, v93
	s_waitcnt lgkmcnt(4)
	s_nop 0
	v_mfma_f32_16x16x32_bf16 v[38:41], v[38:41], v[34:37], 0
	s_waitcnt lgkmcnt(3)
	v_mfma_f32_16x16x32_bf16 v[42:45], v[42:45], v[34:37], 0
	s_waitcnt lgkmcnt(2)
	v_mfma_f32_16x16x32_bf16 v[46:49], v[46:49], v[34:37], 0
	s_waitcnt lgkmcnt(1)
	v_mfma_f32_16x16x32_bf16 v[34:37], v[50:53], v[34:37], 0
	v_cvt_pk_bf16_f32 v50, v88, v89
	v_cvt_pk_bf16_f32 v51, v90, v91
	v_cvt_pk_bf16_f32 v52, v84, v85
	v_cvt_pk_bf16_f32 v53, v86, v87
	s_waitcnt lgkmcnt(0)
	s_nop 0
	v_mfma_f32_16x16x32_bf16 v[74:77], v[54:57], v[50:53], v[38:41]
	s_nop 2
	ds_read2_b64 v[38:41], v136 offset0:40 offset1:44
	s_waitcnt lgkmcnt(0)
	v_mfma_f32_16x16x32_bf16 v[66:69], v[38:41], v[50:53], v[42:45]
	ds_read2_b64 v[38:41], v135 offset0:72 offset1:76
	s_waitcnt lgkmcnt(0)
	v_mfma_f32_16x16x32_bf16 v[58:61], v[38:41], v[50:53], v[46:49]
	ds_read2_b64 v[38:41], v137 offset0:104 offset1:108
	s_waitcnt lgkmcnt(0)
	v_mfma_f32_16x16x32_bf16 v[34:37], v[38:41], v[50:53], v[34:37]
	ds_read_b128 v[38:41], v102 offset:27648
	ds_read_b128 v[42:45], v100 offset:9216
	ds_read_b128 v[46:49], v100 offset:11520
	ds_read_b128 v[50:53], v100 offset:13824
	ds_read_b128 v[54:57], v100 offset:16128
	ds_read_b128 v[140:143], v102 offset:27712
	ds_read_b128 v[62:65], v100 offset:9280
	ds_read_b128 v[70:73], v100 offset:11584
	ds_read_b128 v[164:167], v100 offset:13888
	ds_read_b128 v[168:171], v100 offset:16192
	s_waitcnt lgkmcnt(8)
	v_mfma_f32_16x16x32_bf16 v[42:45], v[42:45], v[38:41], 0
	s_waitcnt lgkmcnt(7)
	v_mfma_f32_16x16x32_bf16 v[46:49], v[46:49], v[38:41], 0
	s_waitcnt lgkmcnt(6)
	v_mfma_f32_16x16x32_bf16 v[50:53], v[50:53], v[38:41], 0
	s_waitcnt lgkmcnt(3)
	v_mfma_f32_16x16x32_bf16 v[172:175], v[62:65], v[140:143], v[42:45]
	s_waitcnt lgkmcnt(2)
	v_mfma_f32_16x16x32_bf16 v[70:73], v[70:73], v[140:143], v[46:49]
	s_waitcnt lgkmcnt(1)
	v_mfma_f32_16x16x32_bf16 v[62:65], v[164:167], v[140:143], v[50:53]
	ds_read_b128 v[42:45], v100 offset:18432
	ds_read_b128 v[46:49], v100 offset:20736
	s_nop 0
	ds_read_b128 v[50:53], v100 offset:23040
	ds_read_b128 v[164:167], v100 offset:25344
	v_mfma_f32_16x16x32_bf16 v[54:57], v[54:57], v[38:41], 0
	s_waitcnt lgkmcnt(4)
	v_mfma_f32_16x16x32_bf16 v[54:57], v[168:171], v[140:143], v[54:57]
	s_waitcnt lgkmcnt(3)
	v_mfma_f32_16x16x32_bf16 v[42:45], v[42:45], v[38:41], 0
	s_waitcnt lgkmcnt(2)
	v_mfma_f32_16x16x32_bf16 v[46:49], v[46:49], v[38:41], 0
	s_waitcnt lgkmcnt(1)
	v_mfma_f32_16x16x32_bf16 v[168:171], v[50:53], v[38:41], 0
	s_waitcnt lgkmcnt(0)
	v_mfma_f32_16x16x32_bf16 v[38:41], v[164:167], v[38:41], 0
	ds_read_b128 v[50:53], v100 offset:18496
	ds_read_b128 v[164:167], v100 offset:20800
	ds_read_b128 v[176:179], v100 offset:23104
	ds_read_b128 v[180:183], v100 offset:25408
	s_waitcnt lgkmcnt(3)
	v_mfma_f32_16x16x32_bf16 v[50:53], v[50:53], v[140:143], v[42:45]
	s_waitcnt lgkmcnt(2)
	v_mfma_f32_16x16x32_bf16 v[46:49], v[164:167], v[140:143], v[46:49]
	s_waitcnt lgkmcnt(1)
	v_mfma_f32_16x16x32_bf16 v[42:45], v[176:179], v[140:143], v[168:171]
	v_add_u32_e32 v176, s0, v106
	s_waitcnt lgkmcnt(0)
	v_mfma_f32_16x16x32_bf16 v[38:41], v[180:183], v[140:143], v[38:41]
	ds_read_b128 v[140:143], v103 offset:37120
	ds_read_b128 v[164:167], v103 offset:37376
	v_lshl_add_u64 v[168:169], v[108:109], 0, s[0:1]
	v_add_co_u32_e32 v170, vcc, s87, v168
	s_waitcnt lgkmcnt(0)
	v_mul_f32_e32 v164, v172, v164
	v_fmac_f32_e32 v164, v74, v140
	v_cvt_pk_bf16_f32 v74, v164, s0
	v_addc_co_u32_e32 v171, vcc, 0, v169, vcc
	global_store_short v[170:171], v74, off offset:2560
	v_mul_f32_e32 v74, v173, v165
	v_fmac_f32_e32 v74, v75, v141
	v_cvt_pk_bf16_f32 v140, v74, s0
	v_add_co_u32_e32 v74, vcc, s29, v168
	v_or_b32_e32 v164, 0x20000, v176
	s_nop 0
	v_addc_co_u32_e32 v75, vcc, 0, v169, vcc
	global_store_short v[74:75], v140, off offset:2560
	v_mul_f32_e32 v74, v174, v166
	v_fmac_f32_e32 v74, v76, v142
	v_cvt_pk_bf16_f32 v76, v74, s0
	v_add_co_u32_e32 v74, vcc, s33, v168
	v_mov_b32_e32 v165, v1
	s_nop 0
	v_addc_co_u32_e32 v75, vcc, 0, v169, vcc
	global_store_short v[74:75], v76, off offset:2560
	v_mul_f32_e32 v74, v175, v167
	v_fmac_f32_e32 v74, v77, v143
	v_cvt_pk_bf16_f32 v76, v74, s0
	v_add_co_u32_e32 v74, vcc, s88, v168
	v_lshl_add_u64 v[164:165], v[104:105], 0, v[164:165]
	s_nop 0
	v_addc_co_u32_e32 v75, vcc, 0, v169, vcc
	global_store_short v[74:75], v76, off offset:2560
	ds_read_b128 v[74:77], v103 offset:37184
	ds_read_b128 v[140:143], v103 offset:37440
	s_waitcnt lgkmcnt(0)
	v_mul_f32_e32 v70, v70, v140
	v_fmac_f32_e32 v70, v66, v74
	v_cvt_pk_bf16_f32 v66, v70, s0
	global_store_short v[164:165], v66, off offset:2560
	v_mul_f32_e32 v66, v71, v141
	v_fmac_f32_e32 v66, v67, v75
	v_cvt_pk_bf16_f32 v70, v66, s0
	v_add_co_u32_e32 v66, vcc, s94, v164
	v_or_b32_e32 v74, 0x40000, v176
	s_nop 0
	v_addc_co_u32_e32 v67, vcc, 0, v165, vcc
	global_store_short v[66:67], v70, off offset:2560
	v_mul_f32_e32 v66, v72, v142
	v_fmac_f32_e32 v66, v68, v76
	v_cvt_pk_bf16_f32 v68, v66, s0
	v_add_co_u32_e32 v66, vcc, s86, v164
	v_mov_b32_e32 v75, v1
	s_nop 0
	v_addc_co_u32_e32 v67, vcc, 0, v165, vcc
	global_store_short v[66:67], v68, off offset:2560
	v_mul_f32_e32 v66, v73, v143
	v_fmac_f32_e32 v66, v69, v77
	v_cvt_pk_bf16_f32 v68, v66, s0
	v_add_co_u32_e32 v66, vcc, s82, v164
	v_lshl_add_u64 v[74:75], v[104:105], 0, v[74:75]
	s_nop 0
	v_addc_co_u32_e32 v67, vcc, 0, v165, vcc
	global_store_short v[66:67], v68, off offset:2560
	ds_read_b128 v[66:69], v103 offset:37248
	ds_read_b128 v[70:73], v103 offset:37504
	s_waitcnt lgkmcnt(0)
	v_mul_f32_e32 v62, v62, v70
	v_fmac_f32_e32 v62, v58, v66
	v_cvt_pk_bf16_f32 v58, v62, s0
	global_store_short v[74:75], v58, off offset:2560
	v_mul_f32_e32 v58, v63, v71
	v_fmac_f32_e32 v58, v59, v67
	v_cvt_pk_bf16_f32 v62, v58, s0
	v_add_co_u32_e32 v58, vcc, s94, v74
	v_or_b32_e32 v66, 0x60000, v176
	s_nop 0
	v_addc_co_u32_e32 v59, vcc, 0, v75, vcc
	global_store_short v[58:59], v62, off offset:2560
	v_mul_f32_e32 v58, v64, v72
	v_fmac_f32_e32 v58, v60, v68
	v_cvt_pk_bf16_f32 v60, v58, s0
	v_add_co_u32_e32 v58, vcc, s86, v74
	v_mov_b32_e32 v67, v1
	s_nop 0
	v_addc_co_u32_e32 v59, vcc, 0, v75, vcc
	global_store_short v[58:59], v60, off offset:2560
	v_mul_f32_e32 v58, v65, v73
	v_fmac_f32_e32 v58, v61, v69
	v_cvt_pk_bf16_f32 v60, v58, s0
	v_add_co_u32_e32 v58, vcc, s82, v74
	v_lshl_add_u64 v[66:67], v[104:105], 0, v[66:67]
	s_nop 0
	v_addc_co_u32_e32 v59, vcc, 0, v75, vcc
	global_store_short v[58:59], v60, off offset:2560
	ds_read_b128 v[58:61], v103 offset:37312
	ds_read_b128 v[62:65], v103 offset:37568
	s_waitcnt lgkmcnt(0)
	v_mul_f32_e32 v54, v54, v62
	v_fmac_f32_e32 v54, v34, v58
	v_cvt_pk_bf16_f32 v34, v54, s0
	global_store_short v[66:67], v34, off offset:2560
	v_mul_f32_e32 v34, v55, v63
	v_fmac_f32_e32 v34, v35, v59
	v_cvt_pk_bf16_f32 v54, v34, s0
	v_add_co_u32_e32 v34, vcc, s94, v66
	s_nop 1
	v_addc_co_u32_e32 v35, vcc, 0, v67, vcc
	global_store_short v[34:35], v54, off offset:2560
	v_mul_f32_e32 v34, v56, v64
	v_fmac_f32_e32 v34, v36, v60
	v_cvt_pk_bf16_f32 v36, v34, s0
	v_add_co_u32_e32 v34, vcc, s86, v66
	s_nop 1
	v_addc_co_u32_e32 v35, vcc, 0, v67, vcc
	global_store_short v[34:35], v36, off offset:2560
	v_mul_f32_e32 v34, v57, v65
	v_fmac_f32_e32 v34, v37, v61
	v_cvt_pk_bf16_f32 v36, v34, s0
	v_add_co_u32_e32 v34, vcc, s82, v66
	s_add_u32 s0, s0, 0x80000
	s_nop 0
	v_addc_co_u32_e32 v35, vcc, 0, v67, vcc
	global_store_short v[34:35], v36, off offset:2560
	v_max_f32_e32 v34, v120, v120
	v_max_f32_e32 v35, v139, v34
	v_sub_f32_e32 v36, v120, v35
	v_sub_f32_e32 v34, v83, v35
	v_mul_f32_e32 v36, 0x3fb8aa3b, v36
	v_mul_f32_e32 v34, 0x3fb8aa3b, v34
	v_exp_f32_e32 v36, v36
	v_exp_f32_e32 v34, v34
	s_addc_u32 s1, s1, 0
	s_add_u32 s42, s42, 0x500
	v_pk_mul_f32 v[52:53], v[36:37], v[52:53] op_sel_hi:[0,1]
	v_pk_mul_f32 v[50:51], v[36:37], v[50:51] op_sel_hi:[0,1]
	v_pk_mul_f32 v[48:49], v[36:37], v[48:49] op_sel_hi:[0,1]
	v_pk_mul_f32 v[46:47], v[36:37], v[46:47] op_sel_hi:[0,1]
	v_pk_mul_f32 v[44:45], v[36:37], v[44:45] op_sel_hi:[0,1]
	v_pk_mul_f32 v[42:43], v[36:37], v[42:43] op_sel_hi:[0,1]
	v_pk_mul_f32 v[40:41], v[36:37], v[40:41] op_sel_hi:[0,1]
	v_pk_mul_f32 v[38:39], v[36:37], v[38:39] op_sel_hi:[0,1]
	v_pk_fma_f32 v[98:99], v[98:99], v[34:35], v[52:53] op_sel_hi:[1,0,1]
	v_pk_fma_f32 v[96:97], v[96:97], v[34:35], v[50:51] op_sel_hi:[1,0,1]
	v_pk_fma_f32 v[94:95], v[94:95], v[34:35], v[48:49] op_sel_hi:[1,0,1]
	v_pk_fma_f32 v[92:93], v[92:93], v[34:35], v[46:47] op_sel_hi:[1,0,1]
	v_pk_fma_f32 v[90:91], v[90:91], v[34:35], v[44:45] op_sel_hi:[1,0,1]
	v_pk_fma_f32 v[88:89], v[88:89], v[34:35], v[42:43] op_sel_hi:[1,0,1]
	v_pk_fma_f32 v[86:87], v[86:87], v[34:35], v[40:41] op_sel_hi:[1,0,1]
	v_pk_fma_f32 v[84:85], v[84:85], v[34:35], v[38:39] op_sel_hi:[1,0,1]
	v_mul_f32_e32 v120, v82, v34
	v_mul_f32_e32 v34, v138, v36
	s_addc_u32 s43, s43, 0
	v_pk_add_f32 v[82:83], v[120:121], v[34:35]
	s_cmp_eq_u32 s0, 0xf80000
	s_barrier
	s_cbranch_scc0 .LBB0_465
	s_waitcnt vmcnt(20)
	v_max_f32_e32 v0, v134, v134
	v_max_f32_e32 v44, v83, v83
	v_max_f32_e32 v0, v44, v0
	ds_write_b128 v133, v[2:5]
	ds_write_b128 v133, v[6:9] offset:9216
	ds_write_b128 v133, v[10:13] offset:18432
	ds_write_b128 v133, v[14:17] offset:27648
	ds_write_b128 v132, v[18:21]
	ds_write_b128 v132, v[22:25] offset:9216
	ds_write_b128 v132, v[26:29] offset:18432
	ds_write_b128 v132, v[30:33] offset:27648
	v_sub_f32_e32 v2, v83, v0
	s_waitcnt lgkmcnt(0)
	s_barrier
	ds_write_b32 v128, v82 offset:36864
	v_mul_f32_e32 v34, 0x3fb8aa3b, v2
	s_waitcnt vmcnt(17)
	v_sub_f32_e32 v2, v125, v0
	v_mul_f32_e32 v35, 0x3fb8aa3b, v2
	ds_read_b128 v[2:5], v129 offset:36864
	ds_read_b128 v[6:9], v129 offset:36880
	ds_read_b128 v[10:13], v129 offset:36896
	ds_read_b128 v[14:17], v107
	ds_read_b128 v[18:21], v129 offset:36912
	ds_read_b128 v[22:25], v107 offset:16
	ds_read_b128 v[26:29], v107 offset:32
	ds_read_b128 v[30:33], v107 offset:48
	s_waitcnt lgkmcnt(4)
	v_lshlrev_b32_e32 v36, 16, v14
	v_and_b32_e32 v14, 0xffff0000, v14
	v_mul_f32_e32 v3, v3, v14
	v_fmac_f32_e32 v3, v2, v36
	v_lshlrev_b32_e32 v2, 16, v15
	v_fmac_f32_e32 v3, v4, v2
	v_and_b32_e32 v2, 0xffff0000, v15
	v_fmac_f32_e32 v3, v5, v2
	v_lshlrev_b32_e32 v2, 16, v16
	v_fmac_f32_e32 v3, v6, v2
	v_and_b32_e32 v2, 0xffff0000, v16
	v_fmac_f32_e32 v3, v7, v2
	v_lshlrev_b32_e32 v2, 16, v17
	v_fmac_f32_e32 v3, v8, v2
	v_and_b32_e32 v2, 0xffff0000, v17
	v_fmac_f32_e32 v3, v9, v2
	v_add_f32_e32 v6, 0, v3
	s_waitcnt lgkmcnt(2)
	v_and_b32_e32 v3, 0xffff0000, v22
	v_lshlrev_b32_e32 v2, 16, v22
	v_mul_f32_e32 v7, v11, v3
	v_fmac_f32_e32 v7, v10, v2
	v_lshlrev_b32_e32 v2, 16, v23
	v_fmac_f32_e32 v7, v12, v2
	v_and_b32_e32 v2, 0xffff0000, v23
	v_fmac_f32_e32 v7, v13, v2
	v_lshlrev_b32_e32 v2, 16, v24
	v_fmac_f32_e32 v7, v18, v2
	v_and_b32_e32 v2, 0xffff0000, v24
	v_fmac_f32_e32 v7, v19, v2
	v_lshlrev_b32_e32 v2, 16, v25
	v_fmac_f32_e32 v7, v20, v2
	v_and_b32_e32 v2, 0xffff0000, v25
	v_fmac_f32_e32 v7, v21, v2
	ds_read_b128 v[2:5], v129 offset:36928
	v_add_f32_e32 v10, v6, v7
	ds_read_b128 v[6:9], v129 offset:36944
	s_waitcnt lgkmcnt(3)
	v_and_b32_e32 v12, 0xffff0000, v26
	v_lshlrev_b32_e32 v11, 16, v26
	s_waitcnt lgkmcnt(1)
	v_mul_f32_e32 v12, v3, v12
	v_fmac_f32_e32 v12, v2, v11
	v_lshlrev_b32_e32 v2, 16, v27
	v_fmac_f32_e32 v12, v4, v2
	v_and_b32_e32 v2, 0xffff0000, v27
	v_fmac_f32_e32 v12, v5, v2
	v_lshlrev_b32_e32 v2, 16, v28
	s_waitcnt lgkmcnt(0)
	v_fmac_f32_e32 v12, v6, v2
	v_and_b32_e32 v2, 0xffff0000, v28
	v_fmac_f32_e32 v12, v7, v2
	v_lshlrev_b32_e32 v2, 16, v29
	v_fmac_f32_e32 v12, v8, v2
	v_and_b32_e32 v2, 0xffff0000, v29
	v_fmac_f32_e32 v12, v9, v2
	ds_read_b128 v[2:5], v129 offset:36960
	ds_read_b128 v[6:9], v129 offset:36976
	v_add_f32_e32 v10, v10, v12
	v_and_b32_e32 v12, 0xffff0000, v30
	v_lshlrev_b32_e32 v11, 16, v30
	s_waitcnt lgkmcnt(1)
	v_mul_f32_e32 v12, v3, v12
	v_fmac_f32_e32 v12, v2, v11
	v_lshlrev_b32_e32 v2, 16, v31
	v_fmac_f32_e32 v12, v4, v2
	v_and_b32_e32 v2, 0xffff0000, v31
	v_fmac_f32_e32 v12, v5, v2
	v_lshlrev_b32_e32 v2, 16, v32
	s_waitcnt lgkmcnt(0)
	v_fmac_f32_e32 v12, v6, v2
	v_and_b32_e32 v2, 0xffff0000, v32
	v_fmac_f32_e32 v12, v7, v2
	v_lshlrev_b32_e32 v2, 16, v33
	v_fmac_f32_e32 v12, v8, v2
	v_and_b32_e32 v6, 0xffff0000, v33
	ds_read_b128 v[2:5], v107 offset:64
	v_fmac_f32_e32 v12, v9, v6
	ds_read_b128 v[6:9], v129 offset:36992
	v_add_f32_e32 v14, v10, v12
	ds_read_b128 v[10:13], v129 offset:37008
	s_waitcnt lgkmcnt(2)
	v_lshlrev_b32_e32 v15, 16, v2
	v_and_b32_e32 v2, 0xffff0000, v2
	s_waitcnt lgkmcnt(1)
	v_mul_f32_e32 v16, v7, v2
	v_fmac_f32_e32 v16, v6, v15
	v_lshlrev_b32_e32 v2, 16, v3
	v_fmac_f32_e32 v16, v8, v2
	v_and_b32_e32 v2, 0xffff0000, v3
	v_fmac_f32_e32 v16, v9, v2
	v_lshlrev_b32_e32 v2, 16, v4
	s_waitcnt lgkmcnt(0)
	v_fmac_f32_e32 v16, v10, v2
	v_and_b32_e32 v2, 0xffff0000, v4
	v_fmac_f32_e32 v16, v11, v2
	v_lshlrev_b32_e32 v2, 16, v5
	v_fmac_f32_e32 v16, v12, v2
	v_and_b32_e32 v6, 0xffff0000, v5
	ds_read_b128 v[2:5], v107 offset:80
	v_fmac_f32_e32 v16, v13, v6
	ds_read_b128 v[6:9], v129 offset:37024
	ds_read_b128 v[10:13], v129 offset:37040
	v_add_f32_e32 v14, v14, v16
	s_waitcnt lgkmcnt(2)
	v_lshlrev_b32_e32 v15, 16, v2
	v_and_b32_e32 v2, 0xffff0000, v2
	s_waitcnt lgkmcnt(1)
	v_mul_f32_e32 v16, v7, v2
	v_fmac_f32_e32 v16, v6, v15
	v_lshlrev_b32_e32 v2, 16, v3
	v_fmac_f32_e32 v16, v8, v2
	v_and_b32_e32 v2, 0xffff0000, v3
	v_fmac_f32_e32 v16, v9, v2
	v_lshlrev_b32_e32 v2, 16, v4
	s_waitcnt lgkmcnt(0)
	v_fmac_f32_e32 v16, v10, v2
	v_and_b32_e32 v2, 0xffff0000, v4
	v_fmac_f32_e32 v16, v11, v2
	v_lshlrev_b32_e32 v2, 16, v5
	v_fmac_f32_e32 v16, v12, v2
	v_and_b32_e32 v6, 0xffff0000, v5
	ds_read_b128 v[2:5], v107 offset:96
	v_fmac_f32_e32 v16, v13, v6
	ds_read_b128 v[6:9], v129 offset:37056
	ds_read_b128 v[10:13], v129 offset:37072
	v_add_f32_e32 v14, v14, v16
	s_waitcnt lgkmcnt(2)
	v_lshlrev_b32_e32 v15, 16, v2
	v_and_b32_e32 v2, 0xffff0000, v2
	s_waitcnt lgkmcnt(1)
	v_mul_f32_e32 v16, v7, v2
	v_fmac_f32_e32 v16, v6, v15
	v_lshlrev_b32_e32 v2, 16, v3
	v_fmac_f32_e32 v16, v8, v2
	v_and_b32_e32 v2, 0xffff0000, v3
	v_fmac_f32_e32 v16, v9, v2
	v_lshlrev_b32_e32 v2, 16, v4
	s_waitcnt lgkmcnt(0)
	v_fmac_f32_e32 v16, v10, v2
	v_and_b32_e32 v2, 0xffff0000, v4
	v_fmac_f32_e32 v16, v11, v2
	v_lshlrev_b32_e32 v2, 16, v5
	v_fmac_f32_e32 v16, v12, v2
	v_and_b32_e32 v6, 0xffff0000, v5
	ds_read_b128 v[2:5], v107 offset:112
	v_fmac_f32_e32 v16, v13, v6
	ds_read_b128 v[6:9], v129 offset:37088
	ds_read_b128 v[10:13], v129 offset:37104
	v_add_f32_e32 v0, v131, v0
	s_waitcnt lgkmcnt(2)
	v_lshlrev_b32_e32 v15, 16, v2
	v_and_b32_e32 v2, 0xffff0000, v2
	s_waitcnt lgkmcnt(1)
	v_mul_f32_e32 v2, v7, v2
	v_fmac_f32_e32 v2, v6, v15
	v_lshlrev_b32_e32 v6, 16, v3
	v_fmac_f32_e32 v2, v8, v6
	v_and_b32_e32 v3, 0xffff0000, v3
	v_fmac_f32_e32 v2, v9, v3
	v_lshlrev_b32_e32 v3, 16, v4
	s_waitcnt lgkmcnt(0)
	v_fmac_f32_e32 v2, v10, v3
	v_and_b32_e32 v3, 0xffff0000, v4
	v_fmac_f32_e32 v2, v11, v3
	v_lshlrev_b32_e32 v3, 16, v5
	v_fmac_f32_e32 v2, v12, v3
	v_and_b32_e32 v3, 0xffff0000, v5
	v_fmac_f32_e32 v2, v13, v3
	v_exp_f32_e32 v3, v34
	v_exp_f32_e32 v4, v35
	v_mul_f32_e32 v0, 0xbfb8aa3b, v0
	v_add_f32_e32 v14, v14, v16
	v_exp_f32_e32 v0, v0
	v_add_f32_e32 v2, v14, v2
	v_mul_f32_e32 v2, v3, v2
	v_fmac_f32_e32 v2, v130, v4
	v_max_f32_e64 v0, |v2|, v0
	v_rcp_f32_e32 v0, v0
	v_cvt_pk_bf16_f32 v10, v96, v97
	v_cvt_pk_bf16_f32 v11, v98, v99
	v_cvt_pk_bf16_f32 v12, v92, v93
	v_mul_f32_e32 v2, v3, v0
	v_mul_f32_e32 v0, v4, v0
	ds_write2st64_b32 v128, v2, v0 offset0:145 offset1:146
	ds_read2_b64 v[2:5], v127 offset1:4
	ds_read2_b64 v[6:9], v136 offset0:32 offset1:36
	ds_read2_b64 v[14:17], v135 offset0:64 offset1:68
	ds_read2_b64 v[18:21], v137 offset0:96 offset1:100
	ds_read2_b64 v[22:25], v127 offset0:8 offset1:12
	v_cvt_pk_bf16_f32 v13, v94, v95
	v_cvt_pk_bf16_f32 v34, v88, v89
	v_cvt_pk_bf16_f32 v35, v90, v91
	s_waitcnt lgkmcnt(4)
	v_mfma_f32_16x16x32_bf16 v[2:5], v[2:5], v[10:13], 0
	v_cvt_pk_bf16_f32 v36, v84, v85
	v_cvt_pk_bf16_f32 v37, v86, v87
	v_or_b32_e32 v0, s39, v126
	s_waitcnt lgkmcnt(3)
	v_mfma_f32_16x16x32_bf16 v[6:9], v[6:9], v[10:13], 0
	v_lshlrev_b32_e32 v0, 13, v0
	v_lshl_add_u64 v[42:43], s[30:31], 0, v[0:1]
	v_lshl_add_u64 v[42:43], v[42:43], 0, s[2:3]
	s_waitcnt lgkmcnt(2)
	v_mfma_f32_16x16x32_bf16 v[14:17], v[14:17], v[10:13], 0
	v_lshl_add_u64 v[42:43], v[80:81], 1, v[42:43]
	v_readlane_b32 s2, v239, 11
	v_readlane_b32 s4, v239, 12
	s_waitcnt lgkmcnt(1)
	v_mfma_f32_16x16x32_bf16 v[10:13], v[18:21], v[10:13], 0
	ds_read2_b64 v[18:21], v136 offset0:40 offset1:44
	s_waitcnt lgkmcnt(1)
	v_mfma_f32_16x16x32_bf16 v[46:49], v[22:25], v[34:37], v[2:5]
	s_nop 2
	ds_read2_b64 v[2:5], v135 offset0:72 offset1:76
	s_waitcnt lgkmcnt(1)
	v_mfma_f32_16x16x32_bf16 v[30:33], v[18:21], v[34:37], v[6:9]
	ds_read_b128 v[18:21], v100 offset:13824
	s_nop 1
	ds_read2_b64 v[6:9], v137 offset0:104 offset1:108
	s_waitcnt lgkmcnt(2)
	v_mfma_f32_16x16x32_bf16 v[26:29], v[2:5], v[34:37], v[14:17]
	s_nop 2
	ds_read_b128 v[14:17], v100 offset:9216
	s_waitcnt lgkmcnt(1)
	v_mfma_f32_16x16x32_bf16 v[2:5], v[6:9], v[34:37], v[10:13]
	s_nop 2
	ds_read_b128 v[10:13], v102 offset:27648
	s_waitcnt lgkmcnt(0)
	v_mfma_f32_16x16x32_bf16 v[6:9], v[14:17], v[10:13], 0
	ds_read_b128 v[14:17], v100 offset:11520
	ds_read_b128 v[22:25], v100 offset:16128
	ds_read_b128 v[34:37], v100 offset:9280
	ds_read_b128 v[50:53], v102 offset:27712
	ds_read_b128 v[38:41], v100 offset:11584
	s_waitcnt lgkmcnt(4)
	v_mfma_f32_16x16x32_bf16 v[14:17], v[14:17], v[10:13], 0
	ds_read_b128 v[58:61], v100 offset:25344
	ds_read_b128 v[62:65], v100 offset:18496
	ds_read_b128 v[66:69], v100 offset:20800
	s_waitcnt lgkmcnt(4)
	v_mfma_f32_16x16x32_bf16 v[54:57], v[34:37], v[50:53], v[6:9]
	s_nop 2
	ds_read_b128 v[6:9], v100 offset:13888
	s_waitcnt lgkmcnt(4)
	v_mfma_f32_16x16x32_bf16 v[38:41], v[38:41], v[50:53], v[14:17]
	s_nop 2
	ds_read_b128 v[14:17], v100 offset:16192
	v_mfma_f32_16x16x32_bf16 v[18:21], v[18:21], v[10:13], 0
	v_mfma_f32_16x16x32_bf16 v[22:25], v[22:25], v[10:13], 0
	s_waitcnt lgkmcnt(1)
	v_mfma_f32_16x16x32_bf16 v[34:37], v[6:9], v[50:53], v[18:21]
	s_nop 4
	ds_read_b128 v[18:21], v100 offset:18432
	s_waitcnt lgkmcnt(1)
	v_mfma_f32_16x16x32_bf16 v[6:9], v[14:17], v[50:53], v[22:25]
	ds_read_b128 v[14:17], v100 offset:20736
	s_nop 1
	ds_read_b128 v[22:25], v100 offset:23040
	s_waitcnt lgkmcnt(2)
	v_mfma_f32_16x16x32_bf16 v[18:21], v[18:21], v[10:13], 0
	s_waitcnt lgkmcnt(1)
	v_mfma_f32_16x16x32_bf16 v[14:17], v[14:17], v[10:13], 0
	s_waitcnt lgkmcnt(0)
	v_mfma_f32_16x16x32_bf16 v[22:25], v[22:25], v[10:13], 0
	v_mfma_f32_16x16x32_bf16 v[58:61], v[58:61], v[10:13], 0
	v_mfma_f32_16x16x32_bf16 v[10:13], v[62:65], v[50:53], v[18:21]
	ds_read_b128 v[62:65], v100 offset:25408
	s_nop 1
	ds_read_b128 v[18:21], v100 offset:23104
	v_mfma_f32_16x16x32_bf16 v[14:17], v[66:69], v[50:53], v[14:17]
	ds_read_b128 v[66:69], v103 offset:37376
	ds_read_b128 v[70:73], v103 offset:37120
	s_waitcnt lgkmcnt(1)
	v_mul_f32_e32 v0, v54, v66
	s_waitcnt lgkmcnt(0)
	v_fmac_f32_e32 v0, v46, v70
	v_cvt_pk_bf16_f32 v0, v0, s0
	s_mov_b32 s0, 0xf80000
	v_mfma_f32_16x16x32_bf16 v[18:21], v[18:21], v[50:53], v[22:25]
	v_mfma_f32_16x16x32_bf16 v[22:25], v[62:65], v[50:53], v[58:61]
	v_add_co_u32_e32 v50, vcc, s0, v42
	s_nop 1
	v_addc_co_u32_e32 v51, vcc, 0, v43, vcc
	global_store_short v[50:51], v0, off offset:2560
	v_mul_f32_e32 v0, v55, v67
	v_fmac_f32_e32 v0, v47, v71
	v_cvt_pk_bf16_f32 v0, v0, s0
	s_mov_b32 s0, 0xf82000
	v_add_co_u32_e32 v46, vcc, s0, v42
	s_nop 1
	v_addc_co_u32_e32 v47, vcc, 0, v43, vcc
	global_store_short v[46:47], v0, off offset:2560
	v_mul_f32_e32 v0, v56, v68
	v_fmac_f32_e32 v0, v48, v72
	v_cvt_pk_bf16_f32 v0, v0, s0
	s_mov_b32 s0, 0xf84000
	v_add_co_u32_e32 v46, vcc, s0, v42
	s_nop 1
	v_addc_co_u32_e32 v47, vcc, 0, v43, vcc
	global_store_short v[46:47], v0, off offset:2560
	v_mul_f32_e32 v0, v57, v69
	v_fmac_f32_e32 v0, v49, v73
	ds_read_b128 v[46:49], v103 offset:37440
	ds_read_b128 v[50:53], v103 offset:37184
	v_cvt_pk_bf16_f32 v0, v0, s0
	s_mov_b32 s0, 0xf86000
	v_add_co_u32_e32 v54, vcc, s0, v42
	s_nop 1
	v_addc_co_u32_e32 v55, vcc, 0, v43, vcc
	global_store_short v[54:55], v0, off offset:2560
	s_waitcnt lgkmcnt(1)
	v_mul_f32_e32 v0, v38, v46
	s_waitcnt lgkmcnt(0)
	v_fmac_f32_e32 v0, v30, v50
	v_cvt_pk_bf16_f32 v0, v0, s0
	s_mov_b32 s0, 0xfa0000
	v_add_co_u32_e32 v54, vcc, s0, v42
	s_nop 1
	v_addc_co_u32_e32 v55, vcc, 0, v43, vcc
	global_store_short v[54:55], v0, off offset:2560
	v_mul_f32_e32 v0, v39, v47
	v_fmac_f32_e32 v0, v31, v51
	v_cvt_pk_bf16_f32 v0, v0, s0
	s_mov_b32 s0, 0xfa2000
	v_add_co_u32_e32 v30, vcc, s0, v42
	s_nop 1
	v_addc_co_u32_e32 v31, vcc, 0, v43, vcc
	global_store_short v[30:31], v0, off offset:2560
	v_mul_f32_e32 v0, v40, v48
	v_fmac_f32_e32 v0, v32, v52
	v_cvt_pk_bf16_f32 v0, v0, s0
	s_mov_b32 s0, 0xfa4000
	v_add_co_u32_e32 v30, vcc, s0, v42
	s_nop 1
	v_addc_co_u32_e32 v31, vcc, 0, v43, vcc
	global_store_short v[30:31], v0, off offset:2560
	v_mul_f32_e32 v0, v41, v49
	v_fmac_f32_e32 v0, v33, v53
	ds_read_b128 v[30:33], v103 offset:37504
	ds_read_b128 v[38:41], v103 offset:37248
	v_cvt_pk_bf16_f32 v0, v0, s0
	s_mov_b32 s0, 0xfa6000
	v_add_co_u32_e32 v46, vcc, s0, v42
	s_nop 1
	v_addc_co_u32_e32 v47, vcc, 0, v43, vcc
	global_store_short v[46:47], v0, off offset:2560
	s_waitcnt lgkmcnt(1)
	v_mul_f32_e32 v0, v34, v30
	s_waitcnt lgkmcnt(0)
	v_fmac_f32_e32 v0, v26, v38
	v_cvt_pk_bf16_f32 v0, v0, s0
	s_mov_b32 s0, 0xfc0000
	v_add_co_u32_e32 v46, vcc, s0, v42
	s_nop 1
	v_addc_co_u32_e32 v47, vcc, 0, v43, vcc
	global_store_short v[46:47], v0, off offset:2560
	v_mul_f32_e32 v0, v35, v31
	v_fmac_f32_e32 v0, v27, v39
	v_cvt_pk_bf16_f32 v0, v0, s0
	s_mov_b32 s0, 0xfc2000
	v_add_co_u32_e32 v26, vcc, s0, v42
	s_nop 1
	v_addc_co_u32_e32 v27, vcc, 0, v43, vcc
	global_store_short v[26:27], v0, off offset:2560
	v_mul_f32_e32 v0, v36, v32
	v_fmac_f32_e32 v0, v28, v40
	v_cvt_pk_bf16_f32 v0, v0, s0
	s_mov_b32 s0, 0xfc4000
	v_add_co_u32_e32 v26, vcc, s0, v42
	s_nop 1
	v_addc_co_u32_e32 v27, vcc, 0, v43, vcc
	global_store_short v[26:27], v0, off offset:2560
	v_mul_f32_e32 v0, v37, v33
	v_fmac_f32_e32 v0, v29, v41
	ds_read_b128 v[26:29], v103 offset:37568
	ds_read_b128 v[30:33], v103 offset:37312
	v_cvt_pk_bf16_f32 v0, v0, s0
	s_mov_b32 s0, 0xfc6000
	v_add_co_u32_e32 v34, vcc, s0, v42
	s_nop 1
	v_addc_co_u32_e32 v35, vcc, 0, v43, vcc
	global_store_short v[34:35], v0, off offset:2560
	s_waitcnt lgkmcnt(1)
	v_mul_f32_e32 v0, v6, v26
	s_waitcnt lgkmcnt(0)
	v_fmac_f32_e32 v0, v2, v30
	v_cvt_pk_bf16_f32 v0, v0, s0
	s_mov_b32 s0, 0xfe0000
	v_add_co_u32_e32 v34, vcc, s0, v42
	s_nop 1
	v_addc_co_u32_e32 v35, vcc, 0, v43, vcc
	global_store_short v[34:35], v0, off offset:2560
	v_mul_f32_e32 v0, v7, v27
	v_fmac_f32_e32 v0, v3, v31
	v_cvt_pk_bf16_f32 v0, v0, s0
	s_mov_b32 s0, 0xfe2000
	v_add_co_u32_e32 v2, vcc, s0, v42
	s_nop 1
	v_addc_co_u32_e32 v3, vcc, 0, v43, vcc
	global_store_short v[2:3], v0, off offset:2560
	v_mul_f32_e32 v0, v8, v28
	v_fmac_f32_e32 v0, v4, v32
	v_cvt_pk_bf16_f32 v0, v0, s0
	s_mov_b32 s0, 0xfe4000
	v_add_co_u32_e32 v2, vcc, s0, v42
	s_nop 1
	v_addc_co_u32_e32 v3, vcc, 0, v43, vcc
	global_store_short v[2:3], v0, off offset:2560
	v_mul_f32_e32 v0, v9, v29
	v_fmac_f32_e32 v0, v5, v33
	v_cvt_pk_bf16_f32 v0, v0, s0
	s_mov_b32 s0, 0xfe6000
	v_add_co_u32_e32 v6, vcc, s0, v42
	v_readlane_b32 s0, v239, 53
	v_max_f32_e32 v2, v125, v125
	s_lshl_b32 s0, s0, 3
	v_max_f32_e32 v3, v44, v2
	s_add_i32 s0, s38, s0
	v_sub_f32_e32 v2, v125, v3
	s_ashr_i32 s1, s0, 31
	v_sub_f32_e32 v4, v83, v3
	v_mul_f32_e32 v2, 0x3fb8aa3b, v2
	s_lshl_b64 s[38:39], s[0:1], 16
	v_exp_f32_e32 v2, v2
	v_mul_f32_e32 v4, 0x3fb8aa3b, v4
	s_add_u32 s2, s2, s38
	v_exp_f32_e32 v4, v4
	s_addc_u32 s39, s4, s39
	s_lshl_b32 s38, s40, 14
	s_add_u32 s38, s2, s38
	v_addc_co_u32_e32 v7, vcc, 0, v43, vcc
	s_addc_u32 s39, s39, 0
	global_store_short v[6:7], v0, off offset:2560
	v_pk_mul_f32 v[6:7], v[2:3], v[12:13] op_sel_hi:[0,1]
	v_pk_mul_f32 v[8:9], v[2:3], v[10:11] op_sel_hi:[0,1]
	v_pk_mul_f32 v[12:13], v[2:3], v[14:15] op_sel_hi:[0,1]
	v_pk_mul_f32 v[14:15], v[2:3], v[20:21] op_sel_hi:[0,1]
	v_pk_mul_f32 v[20:21], v[2:3], v[22:23] op_sel_hi:[0,1]
	v_lshl_add_u64 v[22:23], v[80:81], 2, s[38:39]
	v_lshlrev_b32_e32 v0, 10, v101
	v_pk_fma_f32 v[6:7], v[4:5], v[98:99], v[6:7] op_sel_hi:[0,1,1]
	v_pk_fma_f32 v[8:9], v[4:5], v[96:97], v[8:9] op_sel_hi:[0,1,1]
	v_lshl_add_u64 v[22:23], v[22:23], 0, v[0:1]
	s_barrier
	global_store_dword v[22:23], v8, off
	global_store_dword v[22:23], v9, off offset:256
	global_store_dword v[22:23], v6, off offset:512
	global_store_dword v[22:23], v7, off offset:768
	v_add_co_u32_e32 v6, vcc, s93, v22
	v_pk_mul_f32 v[10:11], v[2:3], v[16:17] op_sel_hi:[0,1]
	s_nop 0
	v_addc_co_u32_e32 v7, vcc, 0, v23, vcc
	v_add_co_u32_e32 v8, vcc, s94, v22
	v_pk_fma_f32 v[12:13], v[4:5], v[92:93], v[12:13] op_sel_hi:[0,1,1]
	v_pk_mul_f32 v[16:17], v[2:3], v[18:19] op_sel_hi:[0,1]
	v_addc_co_u32_e32 v9, vcc, 0, v23, vcc
	v_pk_fma_f32 v[10:11], v[4:5], v[94:95], v[10:11] op_sel_hi:[0,1,1]
	v_pk_fma_f32 v[14:15], v[4:5], v[90:91], v[14:15] op_sel_hi:[0,1,1]
	v_pk_fma_f32 v[16:17], v[4:5], v[88:89], v[16:17] op_sel_hi:[0,1,1]
	global_store_dword v[8:9], v12, off offset:-4096
	global_store_dword v[6:7], v13, off offset:256
	global_store_dword v[6:7], v10, off offset:512
	global_store_dword v[6:7], v11, off offset:768
	global_store_dword v[8:9], v16, off
	global_store_dword v[8:9], v17, off offset:256
	global_store_dword v[8:9], v14, off offset:512
	global_store_dword v[8:9], v15, off offset:768
	v_add_co_u32_e32 v6, vcc, 0x3000, v22
	v_pk_mul_f32 v[18:19], v[2:3], v[24:25] op_sel_hi:[0,1]
	s_nop 0
	v_addc_co_u32_e32 v7, vcc, 0, v23, vcc
	v_pk_fma_f32 v[20:21], v[4:5], v[84:85], v[20:21] op_sel_hi:[0,1,1]
	v_cmp_gt_u32_e32 vcc, 64, v79
	v_pk_fma_f32 v[18:19], v[4:5], v[86:87], v[18:19] op_sel_hi:[0,1,1]
	global_store_dword v[6:7], v20, off
	global_store_dword v[6:7], v21, off offset:256
	global_store_dword v[6:7], v18, off offset:512
	global_store_dword v[6:7], v19, off offset:768
	s_and_saveexec_b64 s[38:39], vcc
	s_cbranch_execz .LBB0_469
	s_lshl_b64 s[42:43], s[0:1], 10
	s_add_u32 s1, s24, s42
	s_addc_u32 s2, s25, s43
	s_lshl_b32 s41, s40, 8
	v_mov_b32_e32 v83, v119
	v_mov_b32_e32 v5, v2
	s_add_u32 s42, s1, s41
	v_pk_mul_f32 v[4:5], v[82:83], v[4:5]
	s_addc_u32 s43, s2, 0
	v_lshlrev_b32_e32 v0, 2, v78
	v_add_f32_e32 v2, v4, v5
	v_lshl_add_u64 v[4:5], s[42:43], 0, v[0:1]
	v_add_co_u32_e32 v4, vcc, 0x4950000, v4
	s_nop 1
	v_addc_co_u32_e32 v5, vcc, 0, v5, vcc
	v_cmp_eq_u32_e32 vcc, 0, v78
	global_store_dword v[4:5], v2, off
	s_and_b64 exec, exec, vcc
	s_cbranch_execz .LBB0_469
	s_mul_hi_i32 s41, s0, 0xfffffc10
	s_mulk_i32 s0, 0xfc10
	s_add_u32 s0, s1, s0
	s_addc_u32 s1, s2, s41
	s_lshl_b32 s2, s40, 2
	s_add_u32 s0, s0, s2
	s_waitcnt vmcnt(49)
	v_add_f32_e32 v0, v117, v3
	s_addc_u32 s1, s1, 0
	global_store_dword v147, v0, s[0:1]
